# hyena st1/st2 entry: skip the second of two back-to-back workgroup barriers (stage-end barrier already covers it)
# baseline (speedup 1.0000x reference)
; HD float2 cmul(float2 a, float2 b){ return make_float2(a.x*b.x - a.y*b.y, a.x*b.y + a.y*b.x); }
; HD void fwd12_padded(float2* Z, const float2* twA, const float2* twB, int t, float2 a0, float2 a1){
;   float2 w1=cmul(twA[t>>6],twB[t&63]), w2=cmul(w1,w1), w3=cmul(w2,w1);
;   Z[t]=make_float2(a0.x+a1.x,a0.y+a1.y);
;   Z[t+4096]=cmul(make_float2(a0.x+a1.y,a0.y-a1.x),w1);
;   Z[t+8192]=cmul(make_float2(a0.x-a1.x,a0.y-a1.y),w2);
;   Z[t+12288]=cmul(make_float2(a0.x-a1.y,a0.y+a1.x),w3);
; }
; __device__ __forceinline__ void phase_hyena(KP kp_, int hf){ asm volatile("" : "+s"(kp_)); const Params p=load_params(kp_);
;     ...
;       __syncthreads();
;       if (st==0){ fft_pass<false,12>(Z,twA,twB,tid); }
;       else if (st==1){ int tq=tid; asm volatile("" : "+v"(tq));
;         _Pragma("unroll 4") for (int i=0;i<8;++i){ int t=tq+512*i;
;           float2 a0=make_float2(hconv3(rv,t,wv0,wv1,wv2,bv_), hconv3(rv+8192,t,wv0,wv1,wv2,bv_));
;           float2 a1=make_float2(hconv3(rv,t+4096,wv0,wv1,wv2,bv_), hconv3(rv+8192,t+4096,wv0,wv1,wv2,bv_));
;           fwd12_padded(Z,twA,twB,t,a0,a1); }
;         __syncthreads();
;       } else { int tq=tid; asm volatile("" : "+v"(tq));
;         _Pragma("unroll 4") for (int i=0;i<8;++i){ int t=tq+512*i; fwd12_padded(Z,twA,twB,t,Zs[t],Zs[t+4096]); }
;         __syncthreads();
.LBB0_1319:
	s_mov_b64 s[12:13], -1
	s_and_b64 vcc, exec, s[68:69]
	s_cbranch_vccnz .Lmy_nobar
	s_barrier
.Lmy_nobar:
	s_cbranch_vccz .LBB0_1329
	s_cmp_lg_u32 s89, 1
	s_cbranch_scc0 .LBB0_1324
	v_lshlrev_b32_e32 v15, 3, v86
	v_mov_b32_e32 v0, v15
	v_add_u32_e32 v1, 0x1000, v15
	v_add_u32_e32 v2, 0x2000, v15
	v_add_u32_e32 v4, 0x3000, v15
	v_add_u32_e32 v5, 0x4000, v15
	v_add_u32_e32 v6, 0x5000, v15
	v_add_u32_e32 v7, 0x6000, v15
	v_add_u32_e32 v8, 0x7000, v15
	s_add_u32 s12, s80, 0x8000
	s_addc_u32 s13, s81, 0
	global_load_dwordx2 v[104:105], v0, s[80:81] sc1
	global_load_dwordx2 v[106:107], v0, s[12:13] sc1
	global_load_dwordx2 v[108:109], v1, s[80:81] sc1
	global_load_dwordx2 v[110:111], v1, s[12:13] sc1
	global_load_dwordx2 v[112:113], v2, s[80:81] sc1
	global_load_dwordx2 v[114:115], v2, s[12:13] sc1
	global_load_dwordx2 v[116:117], v4, s[80:81] sc1
	global_load_dwordx2 v[118:119], v4, s[12:13] sc1
	global_load_dwordx2 v[120:121], v5, s[80:81] sc1
	global_load_dwordx2 v[122:123], v5, s[12:13] sc1
	global_load_dwordx2 v[124:125], v6, s[80:81] sc1
	global_load_dwordx2 v[126:127], v6, s[12:13] sc1
	global_load_dwordx2 v[134:135], v7, s[80:81] sc1
	global_load_dwordx2 v[136:137], v7, s[12:13] sc1
	global_load_dwordx2 v[138:139], v8, s[80:81] sc1
	global_load_dwordx2 v[140:141], v8, s[12:13] sc1
	v_lshlrev_b32_e32 v12, 3, v86
	v_add_u32_e32 v13, 0x10000, v12
	v_lshrrev_b32_e32 v14, 6, v86
	v_lshl_add_u32 v14, v14, 3, s88
	v_and_b32_e32 v15, 63, v86
	v_lshl_add_u32 v15, v15, 3, s91
	ds_read_b64 v[10:11], v15
	ds_read_b64 v[58:59], v14 offset:0
	ds_read_b64 v[60:61], v14 offset:64
	ds_read_b64 v[62:63], v14 offset:128
	ds_read_b64 v[64:65], v14 offset:192
	ds_read_b64 v[66:67], v14 offset:256
	ds_read_b64 v[68:69], v14 offset:320
	ds_read_b64 v[70:71], v14 offset:384
	ds_read_b64 v[72:73], v14 offset:448
	s_waitcnt lgkmcnt(0)
	v_pk_mul_f32 v[222:223], v[58:59], v[10:11] op_sel:[1,1] op_sel_hi:[1,0]
	v_pk_fma_f32 v[22:23], v[58:59], v[10:11], v[222:223] op_sel:[0,0,0] op_sel_hi:[0,1,1] neg_lo:[0,0,1]
	v_pk_mul_f32 v[222:223], v[22:23], v[22:23] op_sel:[1,1] op_sel_hi:[1,0]
	v_pk_fma_f32 v[24:25], v[22:23], v[22:23], v[222:223] op_sel:[0,0,0] op_sel_hi:[0,1,1] neg_lo:[0,0,1]
	v_pk_mul_f32 v[222:223], v[24:25], v[22:23] op_sel:[1,1] op_sel_hi:[1,0]
	v_pk_fma_f32 v[26:27], v[24:25], v[22:23], v[222:223] op_sel:[0,0,0] op_sel_hi:[0,1,1] neg_lo:[0,0,1]
	s_waitcnt vmcnt(14)
	v_pk_add_f32 v[84:85], v[104:105], v[106:107]
	ds_write_b64 v12, v[84:85] offset:0
	v_pk_add_f32 v[74:75], v[104:105], v[106:107] op_sel:[0,1] op_sel_hi:[1,0] neg_hi:[0,1]
	v_pk_mul_f32 v[222:223], v[74:75], v[22:23] op_sel:[1,1] op_sel_hi:[1,0]
	v_pk_fma_f32 v[84:85], v[74:75], v[22:23], v[222:223] op_sel:[0,0,0] op_sel_hi:[0,1,1] neg_lo:[0,0,1]
	ds_write_b64 v12, v[84:85] offset:32768
	v_pk_add_f32 v[74:75], v[104:105], v[106:107] neg_lo:[0,1] neg_hi:[0,1]
	v_pk_mul_f32 v[222:223], v[74:75], v[24:25] op_sel:[1,1] op_sel_hi:[1,0]
	v_pk_fma_f32 v[84:85], v[74:75], v[24:25], v[222:223] op_sel:[0,0,0] op_sel_hi:[0,1,1] neg_lo:[0,0,1]
	ds_write_b64 v13, v[84:85] offset:0
	v_pk_add_f32 v[74:75], v[104:105], v[106:107] op_sel:[0,1] op_sel_hi:[1,0] neg_lo:[0,1]
	v_pk_mul_f32 v[222:223], v[74:75], v[26:27] op_sel:[1,1] op_sel_hi:[1,0]
	v_pk_fma_f32 v[84:85], v[74:75], v[26:27], v[222:223] op_sel:[0,0,0] op_sel_hi:[0,1,1] neg_lo:[0,0,1]
	ds_write_b64 v13, v[84:85] offset:32768
	v_pk_mul_f32 v[222:223], v[60:61], v[10:11] op_sel:[1,1] op_sel_hi:[1,0]
	v_pk_fma_f32 v[22:23], v[60:61], v[10:11], v[222:223] op_sel:[0,0,0] op_sel_hi:[0,1,1] neg_lo:[0,0,1]
	v_pk_mul_f32 v[222:223], v[22:23], v[22:23] op_sel:[1,1] op_sel_hi:[1,0]
	v_pk_fma_f32 v[24:25], v[22:23], v[22:23], v[222:223] op_sel:[0,0,0] op_sel_hi:[0,1,1] neg_lo:[0,0,1]
	v_pk_mul_f32 v[222:223], v[24:25], v[22:23] op_sel:[1,1] op_sel_hi:[1,0]
	v_pk_fma_f32 v[26:27], v[24:25], v[22:23], v[222:223] op_sel:[0,0,0] op_sel_hi:[0,1,1] neg_lo:[0,0,1]
	s_waitcnt vmcnt(12)
	v_pk_add_f32 v[84:85], v[108:109], v[110:111]
	ds_write_b64 v12, v[84:85] offset:4096
	v_pk_add_f32 v[74:75], v[108:109], v[110:111] op_sel:[0,1] op_sel_hi:[1,0] neg_hi:[0,1]
	v_pk_mul_f32 v[222:223], v[74:75], v[22:23] op_sel:[1,1] op_sel_hi:[1,0]
	v_pk_fma_f32 v[84:85], v[74:75], v[22:23], v[222:223] op_sel:[0,0,0] op_sel_hi:[0,1,1] neg_lo:[0,0,1]
	ds_write_b64 v12, v[84:85] offset:36864
	v_pk_add_f32 v[74:75], v[108:109], v[110:111] neg_lo:[0,1] neg_hi:[0,1]
	v_pk_mul_f32 v[222:223], v[74:75], v[24:25] op_sel:[1,1] op_sel_hi:[1,0]
	v_pk_fma_f32 v[84:85], v[74:75], v[24:25], v[222:223] op_sel:[0,0,0] op_sel_hi:[0,1,1] neg_lo:[0,0,1]
	ds_write_b64 v13, v[84:85] offset:4096
	v_pk_add_f32 v[74:75], v[108:109], v[110:111] op_sel:[0,1] op_sel_hi:[1,0] neg_lo:[0,1]
	v_pk_mul_f32 v[222:223], v[74:75], v[26:27] op_sel:[1,1] op_sel_hi:[1,0]
	v_pk_fma_f32 v[84:85], v[74:75], v[26:27], v[222:223] op_sel:[0,0,0] op_sel_hi:[0,1,1] neg_lo:[0,0,1]
	ds_write_b64 v13, v[84:85] offset:36864
	v_pk_mul_f32 v[222:223], v[62:63], v[10:11] op_sel:[1,1] op_sel_hi:[1,0]
	v_pk_fma_f32 v[22:23], v[62:63], v[10:11], v[222:223] op_sel:[0,0,0] op_sel_hi:[0,1,1] neg_lo:[0,0,1]
	v_pk_mul_f32 v[222:223], v[22:23], v[22:23] op_sel:[1,1] op_sel_hi:[1,0]
	v_pk_fma_f32 v[24:25], v[22:23], v[22:23], v[222:223] op_sel:[0,0,0] op_sel_hi:[0,1,1] neg_lo:[0,0,1]
	v_pk_mul_f32 v[222:223], v[24:25], v[22:23] op_sel:[1,1] op_sel_hi:[1,0]
	v_pk_fma_f32 v[26:27], v[24:25], v[22:23], v[222:223] op_sel:[0,0,0] op_sel_hi:[0,1,1] neg_lo:[0,0,1]
	s_waitcnt vmcnt(10)
; HD float2 cmul(float2 a, float2 b){ return make_float2(a.x*b.x - a.y*b.y, a.x*b.y + a.y*b.x); }
; HD void fwd12_padded(float2* Z, const float2* twA, const float2* twB, int t, float2 a0, float2 a1){
;   float2 w1=cmul(twA[t>>6],twB[t&63]), w2=cmul(w1,w1), w3=cmul(w2,w1);
;   Z[t]=make_float2(a0.x+a1.x,a0.y+a1.y);
;   Z[t+4096]=cmul(make_float2(a0.x+a1.y,a0.y-a1.x),w1);
;   Z[t+8192]=cmul(make_float2(a0.x-a1.x,a0.y-a1.y),w2);
;   Z[t+12288]=cmul(make_float2(a0.x-a1.y,a0.y+a1.x),w3);
; }
; __device__ __forceinline__ void phase_hyena(KP kp_, int hf){ asm volatile("" : "+s"(kp_)); const Params p=load_params(kp_);
;     ...
;       } else { int tq=tid; asm volatile("" : "+v"(tq));
;         _Pragma("unroll 4") for (int i=0;i<8;++i){ int t=tq+512*i; fwd12_padded(Z,twA,twB,t,Zs[t],Zs[t+4096]); }
;         __syncthreads();
	v_pk_add_f32 v[84:85], v[112:113], v[114:115]
	ds_write_b64 v12, v[84:85] offset:8192
	v_pk_add_f32 v[74:75], v[112:113], v[114:115] op_sel:[0,1] op_sel_hi:[1,0] neg_hi:[0,1]
	v_pk_mul_f32 v[222:223], v[74:75], v[22:23] op_sel:[1,1] op_sel_hi:[1,0]
	v_pk_fma_f32 v[84:85], v[74:75], v[22:23], v[222:223] op_sel:[0,0,0] op_sel_hi:[0,1,1] neg_lo:[0,0,1]
	ds_write_b64 v12, v[84:85] offset:40960
	v_pk_add_f32 v[74:75], v[112:113], v[114:115] neg_lo:[0,1] neg_hi:[0,1]
	v_pk_mul_f32 v[222:223], v[74:75], v[24:25] op_sel:[1,1] op_sel_hi:[1,0]
	v_pk_fma_f32 v[84:85], v[74:75], v[24:25], v[222:223] op_sel:[0,0,0] op_sel_hi:[0,1,1] neg_lo:[0,0,1]
	ds_write_b64 v13, v[84:85] offset:8192
	v_pk_add_f32 v[74:75], v[112:113], v[114:115] op_sel:[0,1] op_sel_hi:[1,0] neg_lo:[0,1]
	v_pk_mul_f32 v[222:223], v[74:75], v[26:27] op_sel:[1,1] op_sel_hi:[1,0]
	v_pk_fma_f32 v[84:85], v[74:75], v[26:27], v[222:223] op_sel:[0,0,0] op_sel_hi:[0,1,1] neg_lo:[0,0,1]
	ds_write_b64 v13, v[84:85] offset:40960
	v_pk_mul_f32 v[222:223], v[64:65], v[10:11] op_sel:[1,1] op_sel_hi:[1,0]
	v_pk_fma_f32 v[22:23], v[64:65], v[10:11], v[222:223] op_sel:[0,0,0] op_sel_hi:[0,1,1] neg_lo:[0,0,1]
	v_pk_mul_f32 v[222:223], v[22:23], v[22:23] op_sel:[1,1] op_sel_hi:[1,0]
	v_pk_fma_f32 v[24:25], v[22:23], v[22:23], v[222:223] op_sel:[0,0,0] op_sel_hi:[0,1,1] neg_lo:[0,0,1]
	v_pk_mul_f32 v[222:223], v[24:25], v[22:23] op_sel:[1,1] op_sel_hi:[1,0]
	v_pk_fma_f32 v[26:27], v[24:25], v[22:23], v[222:223] op_sel:[0,0,0] op_sel_hi:[0,1,1] neg_lo:[0,0,1]
	s_waitcnt vmcnt(8)
	v_pk_add_f32 v[84:85], v[116:117], v[118:119]
	ds_write_b64 v12, v[84:85] offset:12288
	v_pk_add_f32 v[74:75], v[116:117], v[118:119] op_sel:[0,1] op_sel_hi:[1,0] neg_hi:[0,1]
	v_pk_mul_f32 v[222:223], v[74:75], v[22:23] op_sel:[1,1] op_sel_hi:[1,0]
	v_pk_fma_f32 v[84:85], v[74:75], v[22:23], v[222:223] op_sel:[0,0,0] op_sel_hi:[0,1,1] neg_lo:[0,0,1]
	ds_write_b64 v12, v[84:85] offset:45056
	v_pk_add_f32 v[74:75], v[116:117], v[118:119] neg_lo:[0,1] neg_hi:[0,1]
	v_pk_mul_f32 v[222:223], v[74:75], v[24:25] op_sel:[1,1] op_sel_hi:[1,0]
	v_pk_fma_f32 v[84:85], v[74:75], v[24:25], v[222:223] op_sel:[0,0,0] op_sel_hi:[0,1,1] neg_lo:[0,0,1]
	ds_write_b64 v13, v[84:85] offset:12288
	v_pk_add_f32 v[74:75], v[116:117], v[118:119] op_sel:[0,1] op_sel_hi:[1,0] neg_lo:[0,1]
	v_pk_mul_f32 v[222:223], v[74:75], v[26:27] op_sel:[1,1] op_sel_hi:[1,0]
	v_pk_fma_f32 v[84:85], v[74:75], v[26:27], v[222:223] op_sel:[0,0,0] op_sel_hi:[0,1,1] neg_lo:[0,0,1]
	ds_write_b64 v13, v[84:85] offset:45056
	v_pk_mul_f32 v[222:223], v[66:67], v[10:11] op_sel:[1,1] op_sel_hi:[1,0]
	v_pk_fma_f32 v[22:23], v[66:67], v[10:11], v[222:223] op_sel:[0,0,0] op_sel_hi:[0,1,1] neg_lo:[0,0,1]
	v_pk_mul_f32 v[222:223], v[22:23], v[22:23] op_sel:[1,1] op_sel_hi:[1,0]
	v_pk_fma_f32 v[24:25], v[22:23], v[22:23], v[222:223] op_sel:[0,0,0] op_sel_hi:[0,1,1] neg_lo:[0,0,1]
	v_pk_mul_f32 v[222:223], v[24:25], v[22:23] op_sel:[1,1] op_sel_hi:[1,0]
	v_pk_fma_f32 v[26:27], v[24:25], v[22:23], v[222:223] op_sel:[0,0,0] op_sel_hi:[0,1,1] neg_lo:[0,0,1]
	s_waitcnt vmcnt(6)
	v_pk_add_f32 v[84:85], v[120:121], v[122:123]
	ds_write_b64 v12, v[84:85] offset:16384
	v_pk_add_f32 v[74:75], v[120:121], v[122:123] op_sel:[0,1] op_sel_hi:[1,0] neg_hi:[0,1]
	v_pk_mul_f32 v[222:223], v[74:75], v[22:23] op_sel:[1,1] op_sel_hi:[1,0]
	v_pk_fma_f32 v[84:85], v[74:75], v[22:23], v[222:223] op_sel:[0,0,0] op_sel_hi:[0,1,1] neg_lo:[0,0,1]
	ds_write_b64 v12, v[84:85] offset:49152
	v_pk_add_f32 v[74:75], v[120:121], v[122:123] neg_lo:[0,1] neg_hi:[0,1]
	v_pk_mul_f32 v[222:223], v[74:75], v[24:25] op_sel:[1,1] op_sel_hi:[1,0]
	v_pk_fma_f32 v[84:85], v[74:75], v[24:25], v[222:223] op_sel:[0,0,0] op_sel_hi:[0,1,1] neg_lo:[0,0,1]
	ds_write_b64 v13, v[84:85] offset:16384
	v_pk_add_f32 v[74:75], v[120:121], v[122:123] op_sel:[0,1] op_sel_hi:[1,0] neg_lo:[0,1]
	v_pk_mul_f32 v[222:223], v[74:75], v[26:27] op_sel:[1,1] op_sel_hi:[1,0]
	v_pk_fma_f32 v[84:85], v[74:75], v[26:27], v[222:223] op_sel:[0,0,0] op_sel_hi:[0,1,1] neg_lo:[0,0,1]
	ds_write_b64 v13, v[84:85] offset:49152
	v_pk_mul_f32 v[222:223], v[68:69], v[10:11] op_sel:[1,1] op_sel_hi:[1,0]
	v_pk_fma_f32 v[22:23], v[68:69], v[10:11], v[222:223] op_sel:[0,0,0] op_sel_hi:[0,1,1] neg_lo:[0,0,1]
	v_pk_mul_f32 v[222:223], v[22:23], v[22:23] op_sel:[1,1] op_sel_hi:[1,0]
	v_pk_fma_f32 v[24:25], v[22:23], v[22:23], v[222:223] op_sel:[0,0,0] op_sel_hi:[0,1,1] neg_lo:[0,0,1]
	v_pk_mul_f32 v[222:223], v[24:25], v[22:23] op_sel:[1,1] op_sel_hi:[1,0]
	v_pk_fma_f32 v[26:27], v[24:25], v[22:23], v[222:223] op_sel:[0,0,0] op_sel_hi:[0,1,1] neg_lo:[0,0,1]
	s_waitcnt vmcnt(4)
; HD float2 cmul(float2 a, float2 b){ return make_float2(a.x*b.x - a.y*b.y, a.x*b.y + a.y*b.x); }
; HD void fwd12_padded(float2* Z, const float2* twA, const float2* twB, int t, float2 a0, float2 a1){
;   float2 w1=cmul(twA[t>>6],twB[t&63]), w2=cmul(w1,w1), w3=cmul(w2,w1);
;   Z[t]=make_float2(a0.x+a1.x,a0.y+a1.y);
;   Z[t+4096]=cmul(make_float2(a0.x+a1.y,a0.y-a1.x),w1);
;   Z[t+8192]=cmul(make_float2(a0.x-a1.x,a0.y-a1.y),w2);
;   Z[t+12288]=cmul(make_float2(a0.x-a1.y,a0.y+a1.x),w3);
; }
; __device__ __forceinline__ void phase_hyena(KP kp_, int hf){ asm volatile("" : "+s"(kp_)); const Params p=load_params(kp_);
;     ...
;       } else { int tq=tid; asm volatile("" : "+v"(tq));
;         _Pragma("unroll 4") for (int i=0;i<8;++i){ int t=tq+512*i; fwd12_padded(Z,twA,twB,t,Zs[t],Zs[t+4096]); }
;         __syncthreads();
	v_pk_add_f32 v[84:85], v[124:125], v[126:127]
	ds_write_b64 v12, v[84:85] offset:20480
	v_pk_add_f32 v[74:75], v[124:125], v[126:127] op_sel:[0,1] op_sel_hi:[1,0] neg_hi:[0,1]
	v_pk_mul_f32 v[222:223], v[74:75], v[22:23] op_sel:[1,1] op_sel_hi:[1,0]
	v_pk_fma_f32 v[84:85], v[74:75], v[22:23], v[222:223] op_sel:[0,0,0] op_sel_hi:[0,1,1] neg_lo:[0,0,1]
	ds_write_b64 v12, v[84:85] offset:53248
	v_pk_add_f32 v[74:75], v[124:125], v[126:127] neg_lo:[0,1] neg_hi:[0,1]
	v_pk_mul_f32 v[222:223], v[74:75], v[24:25] op_sel:[1,1] op_sel_hi:[1,0]
	v_pk_fma_f32 v[84:85], v[74:75], v[24:25], v[222:223] op_sel:[0,0,0] op_sel_hi:[0,1,1] neg_lo:[0,0,1]
	ds_write_b64 v13, v[84:85] offset:20480
	v_pk_add_f32 v[74:75], v[124:125], v[126:127] op_sel:[0,1] op_sel_hi:[1,0] neg_lo:[0,1]
	v_pk_mul_f32 v[222:223], v[74:75], v[26:27] op_sel:[1,1] op_sel_hi:[1,0]
	v_pk_fma_f32 v[84:85], v[74:75], v[26:27], v[222:223] op_sel:[0,0,0] op_sel_hi:[0,1,1] neg_lo:[0,0,1]
	ds_write_b64 v13, v[84:85] offset:53248
	v_pk_mul_f32 v[222:223], v[70:71], v[10:11] op_sel:[1,1] op_sel_hi:[1,0]
	v_pk_fma_f32 v[22:23], v[70:71], v[10:11], v[222:223] op_sel:[0,0,0] op_sel_hi:[0,1,1] neg_lo:[0,0,1]
	v_pk_mul_f32 v[222:223], v[22:23], v[22:23] op_sel:[1,1] op_sel_hi:[1,0]
	v_pk_fma_f32 v[24:25], v[22:23], v[22:23], v[222:223] op_sel:[0,0,0] op_sel_hi:[0,1,1] neg_lo:[0,0,1]
	v_pk_mul_f32 v[222:223], v[24:25], v[22:23] op_sel:[1,1] op_sel_hi:[1,0]
	v_pk_fma_f32 v[26:27], v[24:25], v[22:23], v[222:223] op_sel:[0,0,0] op_sel_hi:[0,1,1] neg_lo:[0,0,1]
	s_waitcnt vmcnt(2)
	v_pk_add_f32 v[84:85], v[134:135], v[136:137]
	ds_write_b64 v12, v[84:85] offset:24576
	v_pk_add_f32 v[74:75], v[134:135], v[136:137] op_sel:[0,1] op_sel_hi:[1,0] neg_hi:[0,1]
	v_pk_mul_f32 v[222:223], v[74:75], v[22:23] op_sel:[1,1] op_sel_hi:[1,0]
	v_pk_fma_f32 v[84:85], v[74:75], v[22:23], v[222:223] op_sel:[0,0,0] op_sel_hi:[0,1,1] neg_lo:[0,0,1]
	ds_write_b64 v12, v[84:85] offset:57344
	v_pk_add_f32 v[74:75], v[134:135], v[136:137] neg_lo:[0,1] neg_hi:[0,1]
	v_pk_mul_f32 v[222:223], v[74:75], v[24:25] op_sel:[1,1] op_sel_hi:[1,0]
	v_pk_fma_f32 v[84:85], v[74:75], v[24:25], v[222:223] op_sel:[0,0,0] op_sel_hi:[0,1,1] neg_lo:[0,0,1]
	ds_write_b64 v13, v[84:85] offset:24576
	v_pk_add_f32 v[74:75], v[134:135], v[136:137] op_sel:[0,1] op_sel_hi:[1,0] neg_lo:[0,1]
	v_pk_mul_f32 v[222:223], v[74:75], v[26:27] op_sel:[1,1] op_sel_hi:[1,0]
	v_pk_fma_f32 v[84:85], v[74:75], v[26:27], v[222:223] op_sel:[0,0,0] op_sel_hi:[0,1,1] neg_lo:[0,0,1]
	ds_write_b64 v13, v[84:85] offset:57344
	v_pk_mul_f32 v[222:223], v[72:73], v[10:11] op_sel:[1,1] op_sel_hi:[1,0]
	v_pk_fma_f32 v[22:23], v[72:73], v[10:11], v[222:223] op_sel:[0,0,0] op_sel_hi:[0,1,1] neg_lo:[0,0,1]
	v_pk_mul_f32 v[222:223], v[22:23], v[22:23] op_sel:[1,1] op_sel_hi:[1,0]
	v_pk_fma_f32 v[24:25], v[22:23], v[22:23], v[222:223] op_sel:[0,0,0] op_sel_hi:[0,1,1] neg_lo:[0,0,1]
	v_pk_mul_f32 v[222:223], v[24:25], v[22:23] op_sel:[1,1] op_sel_hi:[1,0]
	v_pk_fma_f32 v[26:27], v[24:25], v[22:23], v[222:223] op_sel:[0,0,0] op_sel_hi:[0,1,1] neg_lo:[0,0,1]
	s_waitcnt vmcnt(0)
	v_pk_add_f32 v[84:85], v[138:139], v[140:141]
	ds_write_b64 v12, v[84:85] offset:28672
	v_pk_add_f32 v[74:75], v[138:139], v[140:141] op_sel:[0,1] op_sel_hi:[1,0] neg_hi:[0,1]
	v_pk_mul_f32 v[222:223], v[74:75], v[22:23] op_sel:[1,1] op_sel_hi:[1,0]
	v_pk_fma_f32 v[84:85], v[74:75], v[22:23], v[222:223] op_sel:[0,0,0] op_sel_hi:[0,1,1] neg_lo:[0,0,1]
	ds_write_b64 v12, v[84:85] offset:61440
	v_pk_add_f32 v[74:75], v[138:139], v[140:141] neg_lo:[0,1] neg_hi:[0,1]
	v_pk_mul_f32 v[222:223], v[74:75], v[24:25] op_sel:[1,1] op_sel_hi:[1,0]
	v_pk_fma_f32 v[84:85], v[74:75], v[24:25], v[222:223] op_sel:[0,0,0] op_sel_hi:[0,1,1] neg_lo:[0,0,1]
	ds_write_b64 v13, v[84:85] offset:28672
	v_pk_add_f32 v[74:75], v[138:139], v[140:141] op_sel:[0,1] op_sel_hi:[1,0] neg_lo:[0,1]
	v_pk_mul_f32 v[222:223], v[74:75], v[26:27] op_sel:[1,1] op_sel_hi:[1,0]
	v_pk_fma_f32 v[84:85], v[74:75], v[26:27], v[222:223] op_sel:[0,0,0] op_sel_hi:[0,1,1] neg_lo:[0,0,1]
	ds_write_b64 v13, v[84:85] offset:61440
	s_mov_b32 s12, 0x8000
	s_mov_b64 s[12:13], 0
	s_waitcnt lgkmcnt(0)
	s_barrier
